# attention: row-max reduction and p0 scale/exp of the next tile moved into PV MFMA gaps; only register copies remain after the tile barrier
# baseline (speedup 1.0000x reference)
; #define SBAR() __builtin_amdgcn_sched_barrier(0)
; #define SLOAD(i, k0) do { sr_[i].vs0 = ld8(&Vh[(long)((k0) + sr) * LDK + sc]); sr_[i].vs1 = ld8(&Vh[(long)((k0) + 32 + sr) * LDK + sc]); \
;     sr_[i].ks0 = ld8(&Kh[(long)((k0) + sr) * LDK + sc]); sr_[i].ks1 = ld8(&Kh[(long)((k0) + 32 + sr) * LDK + sc]); } while (0)
; DI void finishSM(f32x16& p0, f32x16& p1, float alpha, float& l_reg, bf16x8& pa0, bf16x8& pa1, bf16x8& pa2, bf16x8& pa3) {
;   for (int r = 0; r < 16; ++r) p1[r] = __builtin_amdgcn_exp2f(p1[r]);
;   float ps = 0; for (int r = 0; r < 16; ++r) ps += p0[r]; for (int r = 0; r < 16; ++r) ps += p1[r];
;   { auto rr = __builtin_amdgcn_permlane32_swap(__float_as_uint(ps), __float_as_uint(ps), false, false);
;     ps = __uint_as_float(rr[0]) + __uint_as_float(rr[1]); }
;   l_reg = l_reg * alpha + ps;
;     ...
;   PK4(p0, 0, pa0); PK4(p0, 8, pa1); PK4(p1, 0, pa2); PK4(p1, 8, pa3);
;     ...
; }
; DI void qkt(f32x16& p0, f32x16& p1, const bf16_t* Ks, const bf16x8* qr, int r32, int hi) {
;   p0 = f32x16{}; p1 = f32x16{};
;   for (int d0 = 0; d0 < 8; ++d0) { int cb = (d0 * 16 + hi * 8) * 2;
;     bf16x8 b0 = *reinterpret_cast<const bf16x8*>((const char*)Ks + KSWZ(r32, cb));
;     bf16x8 b1 = *reinterpret_cast<const bf16x8*>((const char*)Ks + KSWZ(32 + r32, cb));
;     p0 = __builtin_amdgcn_mfma_f32_32x32x16_bf16(b0, qr[d0], p0, 0, 0, 0);
;     p1 = __builtin_amdgcn_mfma_f32_32x32x16_bf16(b1, qr[d0], p1, 0, 0, 0); }
; DI void attn_dense_body(const bf16_t* __restrict__ Qb, const bf16_t* __restrict__ Kh, const bf16_t* __restrict__ Vh, ...
;     ...
;     SBAR(); qkt(pB0, pB1, (bf16_t*)((char*)K_lds + SHM_K), qr, r32, hi);
;     finishSM(pA0, pA1, alA, l_reg, pa0, pa1, pa2, pa3); SBAR();
;     SLOAD(SO, (j + 2) * KVBLK); SBAR();
;     pv_d0(o, vb0, pa0, pa1, pa2, pa3); partialSM(pB0, pB1, m_reg, mnB, alB);
.LBB0_835:
	ds_read_b128 v[64:67], v207 offset:49152
	ds_read_b128 v[68:71], v207 offset:57344
	ds_read_b128 v[232:235], v210 offset:49152
	ds_read_b128 v[236:239], v210 offset:57344
	v_add_f32_e32 v160, 0, v161
	v_add_f32_e32 v160, v175, v160
	s_waitcnt lgkmcnt(3)
	v_mfma_f32_32x32x16_bf16 v[80:95], v[64:67], v[116:119], 0
	v_add_f32_e32 v160, v162, v160
	v_add_f32_e32 v160, v219, v160
	v_add_f32_e32 v160, v174, v160
	v_add_f32_e32 v160, v222, v160
	v_add_f32_e32 v160, v163, v160
	v_add_f32_e32 v160, v173, v160
	v_add_f32_e32 v160, v164, v160
	s_waitcnt lgkmcnt(2)
	v_mfma_f32_32x32x16_bf16 v[64:79], v[68:71], v[116:119], 0
	ds_read_b128 v[240:243], v211 offset:49152
	ds_read_b128 v[244:247], v211 offset:57344
	v_add_f32_e32 v160, v171, v160
	v_add_f32_e32 v160, v165, v160
	v_add_f32_e32 v160, v172, v160
	v_exp_f32_e32 v158, v158
	v_add_f32_e32 v160, v166, v160
	v_exp_f32_e32 v159, v159
	v_add_f32_e32 v160, v169, v160
	s_waitcnt lgkmcnt(3)
	v_mfma_f32_32x32x16_bf16 v[80:95], v[232:235], v[124:127], v[80:95]
	v_exp_f32_e32 v156, v156
	v_add_f32_e32 v160, v167, v160
	v_exp_f32_e32 v157, v157
	v_add_f32_e32 v160, v170, v160
	v_exp_f32_e32 v152, v152
	v_add_f32_e32 v160, v158, v160
	v_exp_f32_e32 v153, v153
	s_waitcnt lgkmcnt(2)
	v_mfma_f32_32x32x16_bf16 v[64:79], v[236:239], v[124:127], v[64:79]
	ds_read_b128 v[232:235], v208 offset:49152
	ds_read_b128 v[236:239], v208 offset:57344
	v_add_f32_e32 v160, v159, v160
	v_exp_f32_e32 v148, v148
	v_add_f32_e32 v160, v156, v160
	v_exp_f32_e32 v149, v149
	v_add_f32_e32 v160, v157, v160
	v_exp_f32_e32 v146, v146
	s_waitcnt lgkmcnt(3)
	v_mfma_f32_32x32x16_bf16 v[80:95], v[240:243], v[120:123], v[80:95]
	v_add_f32_e32 v160, v152, v160
	v_exp_f32_e32 v147, v147
	v_add_f32_e32 v160, v153, v160
	v_exp_f32_e32 v154, v154
	v_add_f32_e32 v160, v148, v160
	v_exp_f32_e32 v155, v155
	v_add_f32_e32 v160, v149, v160
	s_waitcnt lgkmcnt(2)
	v_mfma_f32_32x32x16_bf16 v[64:79], v[244:247], v[120:123], v[64:79]
	ds_read_b128 v[240:243], v209 offset:49152
	ds_read_b128 v[244:247], v209 offset:57344
	v_exp_f32_e32 v150, v150
	v_add_f32_e32 v160, v146, v160
	v_exp_f32_e32 v151, v151
	v_add_f32_e32 v160, v147, v160
	v_exp_f32_e32 v144, v144
	v_add_f32_e32 v160, v154, v160
	s_waitcnt lgkmcnt(3)
	v_mfma_f32_32x32x16_bf16 v[80:95], v[232:235], v[112:115], v[80:95]
	v_exp_f32_e32 v145, v145
	v_add_f32_e32 v160, v155, v160
	v_add_f32_e32 v160, v150, v160
	v_add_f32_e32 v160, v151, v160
	v_add_f32_e32 v160, v144, v160
	v_add_f32_e32 v216, v145, v160
	v_mov_b32_e32 v217, v216
	s_waitcnt lgkmcnt(2)
	v_mfma_f32_32x32x16_bf16 v[64:79], v[236:239], v[112:115], v[64:79]
	ds_read_b128 v[232:235], v212 offset:49152
	ds_read_b128 v[236:239], v212 offset:57344
	v_permlane32_swap_b32_e32 v216, v217
	s_waitcnt lgkmcnt(3)
	v_mfma_f32_32x32x16_bf16 v[80:95], v[240:243], v[108:111], v[80:95]
	s_waitcnt lgkmcnt(2)
	v_mfma_f32_32x32x16_bf16 v[64:79], v[244:247], v[108:111], v[64:79]
	ds_read_b128 v[240:243], v213 offset:49152
	ds_read_b128 v[244:247], v213 offset:57344
	s_waitcnt lgkmcnt(3)
	v_mfma_f32_32x32x16_bf16 v[80:95], v[232:235], v[104:107], v[80:95]
	s_waitcnt lgkmcnt(2)
	v_mfma_f32_32x32x16_bf16 v[64:79], v[236:239], v[104:107], v[64:79]
	ds_read_b128 v[232:235], v214 offset:49152
	ds_read_b128 v[236:239], v214 offset:57344
	s_waitcnt lgkmcnt(3)
	v_mfma_f32_32x32x16_bf16 v[80:95], v[240:243], v[100:103], v[80:95]
	s_waitcnt lgkmcnt(2)
	v_mfma_f32_32x32x16_bf16 v[64:79], v[244:247], v[100:103], v[64:79]
	v_cvt_pk_bf16_f32 v160, v161, v175
	v_cvt_pk_bf16_f32 v161, v162, v219
	v_cvt_pk_bf16_f32 v162, v174, v222
	v_cvt_pk_bf16_f32 v163, v163, v173
	v_cvt_pk_bf16_f32 v164, v164, v171
	v_cvt_pk_bf16_f32 v165, v165, v172
	s_waitcnt lgkmcnt(1)
	v_mfma_f32_32x32x16_bf16 v[80:95], v[232:235], v[96:99], v[80:95]
	v_cvt_pk_bf16_f32 v166, v166, v169
	v_cvt_pk_bf16_f32 v167, v167, v170
	v_cvt_pk_bf16_f32 v170, v158, v159
	v_cvt_pk_bf16_f32 v171, v156, v157
	v_cvt_pk_bf16_f32 v172, v152, v153
	v_cvt_pk_bf16_f32 v173, v148, v149
	v_cvt_pk_bf16_f32 v218, v146, v147
	s_waitcnt lgkmcnt(0)
	v_mfma_f32_32x32x16_bf16 v[64:79], v[236:239], v[96:99], v[64:79]
	v_cvt_pk_bf16_f32 v219, v154, v155
	v_cvt_pk_bf16_f32 v220, v150, v151
	v_permlane32_swap_b32_e32 v160, v162
	v_cvt_pk_bf16_f32 v221, v144, v145
	v_permlane32_swap_b32_e32 v218, v220
	v_permlane32_swap_b32_e32 v161, v163
	v_permlane32_swap_b32_e32 v164, v166
	v_permlane32_swap_b32_e32 v165, v167
	v_permlane32_swap_b32_e32 v170, v172
	v_permlane32_swap_b32_e32 v171, v173
	v_permlane32_swap_b32_e32 v219, v221
	s_waitcnt vmcnt(0)
	ds_write_b128 v203, v[132:135] offset:32768
	ds_write_b128 v206, v[140:143] offset:32768
	s_mov_b32 s0, 0xffff4000
	v_add_co_u32_e32 v144, vcc, s0, v194
	s_movk_i32 s0, 0x8000
	s_nop 0
	v_addc_co_u32_e32 v145, vcc, -1, v195, vcc
	v_add_co_u32_e32 v148, vcc, s0, v194
	s_mov_b32 s0, 0xfeef4000
	s_nop 0
	v_addc_co_u32_e32 v149, vcc, -1, v195, vcc
	v_add_co_u32_e32 v152, vcc, s0, v194
	s_mov_b32 s0, 0xfeef8000
	s_nop 0
	v_addc_co_u32_e32 v153, vcc, -1, v195, vcc
	v_add_co_u32_e32 v156, vcc, s0, v194
	global_load_dwordx4 v[144:147], v[144:145], off
	s_nop 0
	global_load_dwordx4 v[148:151], v[148:149], off
	v_addc_co_u32_e32 v157, vcc, -1, v195, vcc
	global_load_dwordx4 v[152:155], v[152:153], off
	s_nop 0
	global_load_dwordx4 v[156:159], v[156:157], off
	ds_read_b64_tr_b16 v[232:233], v202 offset:0
	ds_read_b64_tr_b16 v[234:235], v202 offset:0x800
	ds_read_b64_tr_b16 v[236:237], v202 offset:0x1000
	ds_read_b64_tr_b16 v[238:239], v202 offset:0x1800
	ds_read_b64_tr_b16 v[240:241], v202 offset:0x2000
	ds_read_b64_tr_b16 v[242:243], v202 offset:0x2800
	ds_read_b64_tr_b16 v[244:245], v202 offset:0x3000
	ds_read_b64_tr_b16 v[246:247], v202 offset:0x3800
	s_waitcnt lgkmcnt(6)
; #define SWRITE(b, i) do { *(bf16x8*)((char*)V_lds + (b) * SHM_V + vst0) = sr_[i].vs0;          \
;     *(bf16x8*)((char*)V_lds + (b) * SHM_V + vst1) = sr_[i].vs1; int kc = sc * 2;               \
;     *(bf16x8*)((char*)K_lds + (b) * SHM_K + KSWZ(sr, kc)) = sr_[i].ks0;                       \
;     *(bf16x8*)((char*)K_lds + (b) * SHM_K + KSWZ(32 + sr, kc)) = sr_[i].ks1; } while (0)
; #define SWAIT() asm volatile("s_waitcnt vmcnt(4)" ::: "memory")
; #define RESC(a) do { if (__any((a) < 1.f)) { if (hi == 0) al_l[r32] = (a); asm volatile("s_waitcnt lgkmcnt(0)" ::: "memory"); \
;     for (int d = 0; d < 4; ++d) for (int r = 0; r < 16; ++r) o[d][r] *= al_l[crow(r, hi)]; } } while (0)
; DI void partialSM(f32x16& p0, f32x16& p1, float& m_reg, float& mn, float& alpha) {
;   constexpr float C = SCALE * 1.4426950408889634f;
;   float pmax = p0[0]; for (int r = 1; r < 16; ++r) pmax = fmaxf(pmax, p0[r]); for (int r = 0; r < 16; ++r) pmax = fmaxf(pmax, p1[r]);
;   { auto rr = __builtin_amdgcn_permlane32_swap(__float_as_uint(pmax), __float_as_uint(pmax), false, false);
;     pmax = fmaxf(__uint_as_float(rr[0]), __uint_as_float(rr[1])); }
;   if (__builtin_expect(__all(pmax - m_reg <= THR / SCALE), 1)) { mn = m_reg; alpha = 1.f; }
;   else { mn = fmaxf(m_reg, pmax); alpha = __builtin_amdgcn_exp2f((m_reg - mn) * C); m_reg = mn; }
;   float mnC = -mn * C;
;   for (int r = 0; r < 16; ++r) p0[r] = fmaf(p0[r], C, mnC); for (int r = 0; r < 16; ++r) p1[r] = fmaf(p1[r], C, mnC);
;   for (int r = 0; r < 16; ++r) p0[r] = __builtin_amdgcn_exp2f(p0[r]);
; DI void attn_dense_body(const bf16_t* __restrict__ Qb, const bf16_t* __restrict__ Kh, const bf16_t* __restrict__ Vh, ...
;     ...
;     pv_d0(o, vb0, pa0, pa1, pa2, pa3); partialSM(pB0, pB1, m_reg, mnB, alB);
;     __syncthreads(); SWAIT(); SWRITE(0, SE);
;     RESC(alB); __syncthreads();
	s_nop 0
	v_mfma_f32_32x32x16_bf16 v[0:15], v[160:163], v[232:235], v[0:15]
	v_max_f32_e32 v248, v81, v81
	v_max_f32_e32 v249, v80, v80
	v_max_f32_e32 v248, v249, v248
	v_max3_f32 v248, v248, v82, v83
	v_max3_f32 v248, v248, v84, v85
	v_max3_f32 v248, v248, v86, v87
	v_max3_f32 v248, v248, v88, v89
	v_max3_f32 v248, v248, v90, v91
	v_max3_f32 v248, v248, v92, v93
	ds_read_b64_tr_b16 v[232:233], v202 offset:0x200
	ds_read_b64_tr_b16 v[234:235], v202 offset:0xa00
	s_waitcnt lgkmcnt(6)
	v_mfma_f32_32x32x16_bf16 v[0:15], v[164:167], v[236:239], v[0:15]
	v_max3_f32 v248, v248, v94, v95
	v_max3_f32 v248, v248, v64, v65
	v_max3_f32 v248, v248, v66, v67
	v_max3_f32 v248, v248, v68, v69
	v_max3_f32 v248, v248, v70, v71
	v_max3_f32 v248, v248, v72, v73
	v_max3_f32 v248, v248, v74, v75
	v_max3_f32 v248, v248, v76, v77
	ds_read_b64_tr_b16 v[236:237], v202 offset:0x1200
	ds_read_b64_tr_b16 v[238:239], v202 offset:0x1a00
	s_waitcnt lgkmcnt(6)
	v_mfma_f32_32x32x16_bf16 v[0:15], v[170:173], v[240:243], v[0:15]
	v_max3_f32 v248, v248, v78, v79
	v_mov_b32_e32 v249, v248
	s_nop 1
	v_permlane32_swap_b32_e32 v248, v249
	v_max_f32_e32 v249, v249, v249
	v_max_f32_e32 v248, v248, v248
	v_max_f32_e32 v248, v248, v249
	v_sub_f32_e32 v249, v248, v168
	v_cmp_ge_f32_e32 vcc, s95, v249
	v_max_f32_e32 v249, v168, v168
	v_max_f32_e32 v248, v249, v248
	ds_read_b64_tr_b16 v[240:241], v202 offset:0x2200
	ds_read_b64_tr_b16 v[242:243], v202 offset:0x2a00
	s_waitcnt lgkmcnt(6)
	v_mfma_f32_32x32x16_bf16 v[0:15], v[218:221], v[244:247], v[0:15]
	v_sub_f32_e32 v249, v168, v248
	v_mul_f32_e32 v249, 0x3e0293ee, v249
	v_exp_f32_e32 v249, v249
	s_cmp_eq_u64 vcc, exec
	s_cselect_b64 s[0:1], -1, 0
	v_cndmask_b32_e64 v250, v248, v168, s[0:1]
	v_mul_f32_e32 v251, 0xbe0293ee, v250
	ds_read_b64_tr_b16 v[244:245], v202 offset:0x3200
	ds_read_b64_tr_b16 v[246:247], v202 offset:0x3a00
	s_waitcnt lgkmcnt(6)
	v_mfma_f32_32x32x16_bf16 v[48:63], v[160:163], v[232:235], v[48:63]
	v_fmamk_f32 v80, v80, 0x3e0293ee, v251
	v_fmamk_f32 v81, v81, 0x3e0293ee, v251
	v_fmamk_f32 v82, v82, 0x3e0293ee, v251
	v_fmamk_f32 v83, v83, 0x3e0293ee, v251
	ds_read_b64_tr_b16 v[232:233], v202 offset:0x400
	ds_read_b64_tr_b16 v[234:235], v202 offset:0xc00
	s_waitcnt lgkmcnt(6)
	v_mfma_f32_32x32x16_bf16 v[48:63], v[164:167], v[236:239], v[48:63]
	v_fmamk_f32 v84, v84, 0x3e0293ee, v251
	v_fmamk_f32 v85, v85, 0x3e0293ee, v251
	v_fmamk_f32 v86, v86, 0x3e0293ee, v251
	v_fmamk_f32 v87, v87, 0x3e0293ee, v251
	ds_read_b64_tr_b16 v[236:237], v202 offset:0x1400
	ds_read_b64_tr_b16 v[238:239], v202 offset:0x1c00
	s_waitcnt lgkmcnt(6)
	v_mfma_f32_32x32x16_bf16 v[48:63], v[170:173], v[240:243], v[48:63]
	v_fmamk_f32 v88, v88, 0x3e0293ee, v251
	v_fmamk_f32 v89, v89, 0x3e0293ee, v251
	v_fmamk_f32 v90, v90, 0x3e0293ee, v251
	v_fmamk_f32 v91, v91, 0x3e0293ee, v251
	ds_read_b64_tr_b16 v[240:241], v202 offset:0x2400
	ds_read_b64_tr_b16 v[242:243], v202 offset:0x2c00
	s_waitcnt lgkmcnt(6)
	v_mfma_f32_32x32x16_bf16 v[48:63], v[218:221], v[244:247], v[48:63]
	v_fmamk_f32 v92, v92, 0x3e0293ee, v251
	v_fmamk_f32 v93, v93, 0x3e0293ee, v251
	v_fmamk_f32 v94, v94, 0x3e0293ee, v251
	v_fmamk_f32 v95, v95, 0x3e0293ee, v251
	ds_read_b64_tr_b16 v[244:245], v202 offset:0x3400
	ds_read_b64_tr_b16 v[246:247], v202 offset:0x3c00
	s_waitcnt lgkmcnt(6)
	v_mfma_f32_32x32x16_bf16 v[32:47], v[160:163], v[232:235], v[32:47]
	v_exp_f32_e32 v80, v80
	v_exp_f32_e32 v81, v81
	ds_read_b64_tr_b16 v[232:233], v202 offset:0x600
	ds_read_b64_tr_b16 v[234:235], v202 offset:0xe00
	s_waitcnt lgkmcnt(6)
	v_mfma_f32_32x32x16_bf16 v[32:47], v[164:167], v[236:239], v[32:47]
	v_exp_f32_e32 v82, v82
	v_exp_f32_e32 v83, v83
	ds_read_b64_tr_b16 v[236:237], v202 offset:0x1600
	ds_read_b64_tr_b16 v[238:239], v202 offset:0x1e00
	s_waitcnt lgkmcnt(6)
	v_mfma_f32_32x32x16_bf16 v[32:47], v[170:173], v[240:243], v[32:47]
	v_exp_f32_e32 v84, v84
	v_exp_f32_e32 v85, v85
	ds_read_b64_tr_b16 v[240:241], v202 offset:0x2600
	ds_read_b64_tr_b16 v[242:243], v202 offset:0x2e00
	s_waitcnt lgkmcnt(6)
	v_mfma_f32_32x32x16_bf16 v[32:47], v[218:221], v[244:247], v[32:47]
	v_exp_f32_e32 v86, v86
	v_exp_f32_e32 v87, v87
	ds_read_b64_tr_b16 v[244:245], v202 offset:0x3600
	ds_read_b64_tr_b16 v[246:247], v202 offset:0x3e00
	s_waitcnt lgkmcnt(6)
	v_mfma_f32_32x32x16_bf16 v[16:31], v[160:163], v[232:235], v[16:31]
	v_exp_f32_e32 v88, v88
	v_exp_f32_e32 v89, v89
	s_waitcnt lgkmcnt(4)
	v_mfma_f32_32x32x16_bf16 v[16:31], v[164:167], v[236:239], v[16:31]
	v_exp_f32_e32 v90, v90
	v_exp_f32_e32 v91, v91
	s_waitcnt lgkmcnt(2)
	v_mfma_f32_32x32x16_bf16 v[16:31], v[170:173], v[240:243], v[16:31]
	v_exp_f32_e32 v92, v92
	v_exp_f32_e32 v93, v93
	s_waitcnt lgkmcnt(0)
	v_mfma_f32_32x32x16_bf16 v[16:31], v[218:221], v[244:247], v[16:31]
	v_exp_f32_e32 v94, v94
	v_exp_f32_e32 v95, v95
	s_barrier
	s_waitcnt vmcnt(4)
	v_cndmask_b32_e64 v218, v249, 1.0, s[0:1]
	v_cmp_gt_f32_e32 vcc, 1.0, v218
	s_waitcnt vmcnt(7)
	ds_write_b128 v204, v[128:131]
	s_waitcnt vmcnt(6)
	ds_write_b128 v205, v[136:139]
	s_cbranch_vccz .LBB0_839
	s_and_saveexec_b64 s[10:11], s[4:5]
	ds_write_b32 v199, v218 offset:128
	s_or_b64 exec, exec, s[10:11]
	s_waitcnt lgkmcnt(0)
	v_add_u32_e32 v161, v198, v180
	ds_read_b128 v[162:165], v161 offset:224
	ds_read_b128 v[170:173], v161 offset:192
	ds_read_b128 v[220:223], v161 offset:160
	ds_read_b128 v[232:235], v161 offset:128
	s_waitcnt lgkmcnt(3)
	v_pk_mul_f32 v[12:13], v[12:13], v[162:163]
	s_waitcnt lgkmcnt(2)
	v_pk_mul_f32 v[8:9], v[8:9], v[170:171]
	s_waitcnt lgkmcnt(1)
	v_pk_mul_f32 v[4:5], v[4:5], v[220:221]
	v_pk_mul_f32 v[14:15], v[14:15], v[164:165]
	v_pk_mul_f32 v[10:11], v[10:11], v[172:173]
	v_pk_mul_f32 v[6:7], v[6:7], v[222:223]
	s_waitcnt lgkmcnt(0)
	v_pk_mul_f32 v[2:3], v[2:3], v[234:235]
	v_pk_mul_f32 v[0:1], v[0:1], v[232:233]
	v_pk_mul_f32 v[60:61], v[60:61], v[162:163]
	v_pk_mul_f32 v[56:57], v[56:57], v[170:171]
	v_pk_mul_f32 v[52:53], v[52:53], v[220:221]
	v_pk_mul_f32 v[62:63], v[62:63], v[164:165]
	v_pk_mul_f32 v[58:59], v[58:59], v[172:173]
	v_pk_mul_f32 v[54:55], v[54:55], v[222:223]
	v_pk_mul_f32 v[50:51], v[50:51], v[234:235]
	v_pk_mul_f32 v[48:49], v[48:49], v[232:233]
	v_pk_mul_f32 v[44:45], v[44:45], v[162:163]
	v_pk_mul_f32 v[40:41], v[40:41], v[170:171]
	v_pk_mul_f32 v[36:37], v[36:37], v[220:221]
	v_pk_mul_f32 v[46:47], v[46:47], v[164:165]
	v_pk_mul_f32 v[42:43], v[42:43], v[172:173]
	v_pk_mul_f32 v[38:39], v[38:39], v[222:223]
	v_pk_mul_f32 v[34:35], v[34:35], v[234:235]
	v_pk_mul_f32 v[32:33], v[32:33], v[232:233]
	v_pk_mul_f32 v[28:29], v[28:29], v[162:163]
	v_pk_mul_f32 v[24:25], v[24:25], v[170:171]
	v_pk_mul_f32 v[20:21], v[20:21], v[220:221]
	v_pk_mul_f32 v[30:31], v[30:31], v[164:165]
	v_pk_mul_f32 v[26:27], v[26:27], v[172:173]
	v_pk_mul_f32 v[22:23], v[22:23], v[222:223]
	v_pk_mul_f32 v[18:19], v[18:19], v[234:235]
	v_pk_mul_f32 v[16:17], v[16:17], v[232:233]
; #define SBAR() __builtin_amdgcn_sched_barrier(0)
; #define SLOAD(i, k0) do { sr_[i].vs0 = ld8(&Vh[(long)((k0) + sr) * LDK + sc]); sr_[i].vs1 = ld8(&Vh[(long)((k0) + 32 + sr) * LDK + sc]); \
;     sr_[i].ks0 = ld8(&Kh[(long)((k0) + sr) * LDK + sc]); sr_[i].ks1 = ld8(&Kh[(long)((k0) + 32 + sr) * LDK + sc]); } while (0)
; DI void partialSM(f32x16& p0, f32x16& p1, float& m_reg, float& mn, float& alpha) {
;     ...
;   for (int r = 0; r < 16; ++r) p0[r] = fmaf(p0[r], C, mnC); for (int r = 0; r < 16; ++r) p1[r] = fmaf(p1[r], C, mnC);
;   for (int r = 0; r < 16; ++r) p0[r] = __builtin_amdgcn_exp2f(p0[r]);
; }
; DI void finishSM(f32x16& p0, f32x16& p1, float alpha, float& l_reg, bf16x8& pa0, bf16x8& pa1, bf16x8& pa2, bf16x8& pa3) {
;   for (int r = 0; r < 16; ++r) p1[r] = __builtin_amdgcn_exp2f(p1[r]);
;   float ps = 0; for (int r = 0; r < 16; ++r) ps += p0[r]; for (int r = 0; r < 16; ++r) ps += p1[r];
;   { auto rr = __builtin_amdgcn_permlane32_swap(__float_as_uint(ps), __float_as_uint(ps), false, false);
;     ps = __uint_as_float(rr[0]) + __uint_as_float(rr[1]); }
;   l_reg = l_reg * alpha + ps;
;     ...
;   PK4(p0, 0, pa0); PK4(p0, 8, pa1); PK4(p1, 0, pa2); PK4(p1, 8, pa3);
; DI void attn_dense_body(const bf16_t* __restrict__ Qb, const bf16_t* __restrict__ Kh, const bf16_t* __restrict__ Vh, ...
;     ...
;     SBAR(); qkt(pA0, pA1, K_lds, qr, r32, hi);
;     finishSM(pB0, pB1, alB, l_reg, pa0, pa1, pa2, pa3); SBAR();
;     if (j + 3 < NT) SLOAD(SE, (j + 3) * KVBLK); SBAR();
.LBB0_839:
	v_mov_b32_e32 v219, v250
	v_mov_b32_e32 v160, v80
	v_mov_b32_e32 v175, v81
	v_mov_b32_e32 v161, v82
	v_mov_b32_e32 v174, v83
	v_mov_b32_e32 v162, v84
	v_mov_b32_e32 v173, v85
	v_mov_b32_e32 v163, v86
	v_mov_b32_e32 v172, v87
	v_mov_b32_e32 v164, v88
	v_mov_b32_e32 v171, v89
	v_mov_b32_e32 v165, v90
	v_mov_b32_e32 v170, v91
	v_mov_b32_e32 v166, v92
	v_mov_b32_e32 v169, v93
	v_mov_b32_e32 v167, v94
	v_mov_b32_e32 v168, v95
	v_fmamk_f32 v236, v64, 0x3e0293ee, v251
	v_fmamk_f32 v237, v65, 0x3e0293ee, v251
	v_fmamk_f32 v238, v66, 0x3e0293ee, v251
	v_fmamk_f32 v239, v67, 0x3e0293ee, v251
	v_fmamk_f32 v240, v68, 0x3e0293ee, v251
	v_fmamk_f32 v222, v69, 0x3e0293ee, v251
	v_fmamk_f32 v223, v70, 0x3e0293ee, v251
	v_fmamk_f32 v231, v71, 0x3e0293ee, v251
	v_fmamk_f32 v232, v72, 0x3e0293ee, v251
	v_fmamk_f32 v233, v73, 0x3e0293ee, v251
	v_fmamk_f32 v234, v74, 0x3e0293ee, v251
	v_fmamk_f32 v235, v75, 0x3e0293ee, v251
	v_fmamk_f32 v221, v76, 0x3e0293ee, v251
	v_fmamk_f32 v241, v77, 0x3e0293ee, v251
	v_fmamk_f32 v242, v78, 0x3e0293ee, v251
	v_fmamk_f32 v220, v79, 0x3e0293ee, v251
	s_waitcnt lgkmcnt(0)
	ds_read_b128 v[64:67], v207 offset:32768
	ds_read_b128 v[68:71], v207 offset:40960
	ds_read_b128 v[244:247], v210 offset:32768
	ds_read_b128 v[248:251], v210 offset:40960
	v_exp_f32_e32 v226, v238
	v_exp_f32_e32 v238, v220
	s_waitcnt lgkmcnt(3)
	v_mfma_f32_32x32x16_bf16 v[80:95], v[64:67], v[116:119], 0
	v_add_f32_e32 v220, 0, v160
	v_add_f32_e32 v220, v175, v220
	v_add_f32_e32 v220, v161, v220
	v_add_f32_e32 v220, v174, v220
	v_add_f32_e32 v220, v162, v220
	v_add_f32_e32 v220, v173, v220
	v_add_f32_e32 v220, v163, v220
	s_waitcnt lgkmcnt(2)
	v_mfma_f32_32x32x16_bf16 v[64:79], v[68:71], v[116:119], 0
	ds_read_b128 v[128:131], v211 offset:32768
	ds_read_b128 v[132:135], v211 offset:40960
	v_add_f32_e32 v220, v172, v220
	v_add_f32_e32 v220, v164, v220
	v_add_f32_e32 v220, v171, v220
	v_add_f32_e32 v220, v165, v220
	v_add_f32_e32 v220, v170, v220
	v_exp_f32_e32 v224, v236
	v_add_f32_e32 v220, v166, v220
	s_waitcnt lgkmcnt(3)
	v_mfma_f32_32x32x16_bf16 v[80:95], v[244:247], v[124:127], v[80:95]
	v_exp_f32_e32 v225, v237
	v_add_f32_e32 v220, v169, v220
	v_add_f32_e32 v220, v167, v220
	v_exp_f32_e32 v227, v239
	v_add_f32_e32 v220, v168, v220
	v_exp_f32_e32 v228, v240
	v_add_f32_e32 v220, v224, v220
	s_waitcnt lgkmcnt(2)
	v_mfma_f32_32x32x16_bf16 v[64:79], v[248:251], v[124:127], v[64:79]
	ds_read_b128 v[244:247], v208 offset:32768
	ds_read_b128 v[248:251], v208 offset:40960
	v_exp_f32_e32 v222, v222
	v_add_f32_e32 v220, v225, v220
	v_exp_f32_e32 v223, v223
	v_add_f32_e32 v220, v226, v220
	v_exp_f32_e32 v229, v231
	v_add_f32_e32 v220, v227, v220
	s_waitcnt lgkmcnt(3)
	v_mfma_f32_32x32x16_bf16 v[80:95], v[128:131], v[120:123], v[80:95]
	v_exp_f32_e32 v231, v232
	v_add_f32_e32 v220, v228, v220
	v_exp_f32_e32 v232, v233
	v_add_f32_e32 v220, v222, v220
	v_exp_f32_e32 v233, v234
	v_add_f32_e32 v220, v223, v220
	v_exp_f32_e32 v234, v235
	s_waitcnt lgkmcnt(2)
	v_mfma_f32_32x32x16_bf16 v[64:79], v[132:135], v[120:123], v[64:79]
	ds_read_b128 v[128:131], v209 offset:32768
	ds_read_b128 v[132:135], v209 offset:40960
	v_add_f32_e32 v220, v229, v220
	v_exp_f32_e32 v235, v221
	v_add_f32_e32 v220, v231, v220
	v_exp_f32_e32 v236, v241
	v_add_f32_e32 v220, v232, v220
	v_exp_f32_e32 v237, v242
	s_waitcnt lgkmcnt(3)
	v_mfma_f32_32x32x16_bf16 v[80:95], v[244:247], v[112:115], v[80:95]
	v_add_f32_e32 v220, v233, v220
	v_add_f32_e32 v220, v234, v220
	v_add_f32_e32 v220, v235, v220
	v_add_f32_e32 v220, v236, v220
	v_add_f32_e32 v220, v237, v220
	v_add_f32_e32 v220, v238, v220
	v_mov_b32_e32 v221, v220
	s_waitcnt lgkmcnt(2)
	v_mfma_f32_32x32x16_bf16 v[64:79], v[248:251], v[112:115], v[64:79]
	ds_read_b128 v[244:247], v212 offset:32768
	ds_read_b128 v[248:251], v212 offset:40960
	v_permlane32_swap_b32_e32 v220, v221
	s_waitcnt lgkmcnt(3)
	v_mfma_f32_32x32x16_bf16 v[80:95], v[128:131], v[108:111], v[80:95]
	s_waitcnt lgkmcnt(2)
	v_mfma_f32_32x32x16_bf16 v[64:79], v[132:135], v[108:111], v[64:79]
	ds_read_b128 v[128:131], v213 offset:32768
	ds_read_b128 v[132:135], v213 offset:40960
	s_waitcnt lgkmcnt(3)
	v_mfma_f32_32x32x16_bf16 v[80:95], v[244:247], v[104:107], v[80:95]
	s_waitcnt lgkmcnt(2)
	v_mfma_f32_32x32x16_bf16 v[64:79], v[248:251], v[104:107], v[64:79]
	ds_read_b128 v[244:247], v214 offset:32768
	ds_read_b128 v[248:251], v214 offset:40960
	s_waitcnt lgkmcnt(3)
	v_mfma_f32_32x32x16_bf16 v[80:95], v[128:131], v[100:103], v[80:95]
	s_waitcnt lgkmcnt(2)
	v_mfma_f32_32x32x16_bf16 v[64:79], v[132:135], v[100:103], v[64:79]
	v_cvt_pk_bf16_f32 v160, v160, v175
	v_cvt_pk_bf16_f32 v161, v161, v174
	v_cvt_pk_bf16_f32 v162, v162, v173
	v_cvt_pk_bf16_f32 v163, v163, v172
	v_cvt_pk_bf16_f32 v164, v164, v171
	v_cvt_pk_bf16_f32 v165, v165, v170
	s_waitcnt lgkmcnt(1)
	v_mfma_f32_32x32x16_bf16 v[80:95], v[244:247], v[96:99], v[80:95]
	v_cvt_pk_bf16_f32 v166, v166, v169
	v_cvt_pk_bf16_f32 v167, v167, v168
	v_cvt_pk_bf16_f32 v168, v224, v225
	v_cvt_pk_bf16_f32 v169, v226, v227
	v_cvt_pk_bf16_f32 v170, v228, v222
	v_cvt_pk_bf16_f32 v171, v223, v229
	v_cvt_pk_bf16_f32 v172, v231, v232
	s_waitcnt lgkmcnt(0)
	v_mfma_f32_32x32x16_bf16 v[64:79], v[248:251], v[96:99], v[64:79]
	v_cvt_pk_bf16_f32 v173, v233, v234
	v_cvt_pk_bf16_f32 v174, v235, v236
	v_cvt_pk_bf16_f32 v175, v237, v238
	v_permlane32_swap_b32_e32 v160, v162
	v_permlane32_swap_b32_e32 v161, v163
	v_permlane32_swap_b32_e32 v164, v166
	v_permlane32_swap_b32_e32 v165, v167
	v_permlane32_swap_b32_e32 v168, v170
	v_permlane32_swap_b32_e32 v169, v171
	v_permlane32_swap_b32_e32 v172, v174
	v_permlane32_swap_b32_e32 v173, v175
	s_waitcnt vmcnt(0)
	ds_write_b128 v203, v[152:155] offset:49152
	ds_write_b128 v206, v[156:159] offset:49152
	s_cmp_ge_u32 s16, s15
	s_cselect_b64 s[10:11], -1, 0
	s_and_b64 vcc, exec, s[10:11]
	s_cbranch_vccnz .LBB0_841
	v_add_co_u32_e32 v128, vcc, 0xffffc000, v194
	s_nop 1
	v_addc_co_u32_e32 v129, vcc, -1, v195, vcc
	v_add_co_u32_e32 v132, vcc, 0xfeefc000, v194
	s_nop 1
	v_addc_co_u32_e32 v133, vcc, -1, v195, vcc
	v_add_co_u32_e32 v140, vcc, 0xfef00000, v194
	global_load_dwordx4 v[128:131], v[128:129], off
	s_nop 0
	global_load_dwordx4 v[132:135], v[132:133], off
	v_addc_co_u32_e32 v141, vcc, -1, v195, vcc
	global_load_dwordx4 v[136:139], v[194:195], off
	s_nop 0
	global_load_dwordx4 v[140:143], v[140:141], off
; #define SWRITE(b, i) do { *(bf16x8*)((char*)V_lds + (b) * SHM_V + vst0) = sr_[i].vs0;          \
;     *(bf16x8*)((char*)V_lds + (b) * SHM_V + vst1) = sr_[i].vs1; int kc = sc * 2;               \
;     *(bf16x8*)((char*)K_lds + (b) * SHM_K + KSWZ(sr, kc)) = sr_[i].ks0;                       \
;     *(bf16x8*)((char*)K_lds + (b) * SHM_K + KSWZ(32 + sr, kc)) = sr_[i].ks1; } while (0)
; #define SWAIT() asm volatile("s_waitcnt vmcnt(4)" ::: "memory")
; #define RESC(a) do { if (__any((a) < 1.f)) { if (hi == 0) al_l[r32] = (a); asm volatile("s_waitcnt lgkmcnt(0)" ::: "memory"); \
;     for (int d = 0; d < 4; ++d) for (int r = 0; r < 16; ++r) o[d][r] *= al_l[crow(r, hi)]; } } while (0)
; DI void partialSM(f32x16& p0, f32x16& p1, float& m_reg, float& mn, float& alpha) {
;   constexpr float C = SCALE * 1.4426950408889634f;
;   float pmax = p0[0]; for (int r = 1; r < 16; ++r) pmax = fmaxf(pmax, p0[r]); for (int r = 0; r < 16; ++r) pmax = fmaxf(pmax, p1[r]);
;   { auto rr = __builtin_amdgcn_permlane32_swap(__float_as_uint(pmax), __float_as_uint(pmax), false, false);
;     pmax = fmaxf(__uint_as_float(rr[0]), __uint_as_float(rr[1])); }
;   if (__builtin_expect(__all(pmax - m_reg <= THR / SCALE), 1)) { mn = m_reg; alpha = 1.f; }
;   else { mn = fmaxf(m_reg, pmax); alpha = __builtin_amdgcn_exp2f((m_reg - mn) * C); m_reg = mn; }
;   float mnC = -mn * C;
;   for (int r = 0; r < 16; ++r) p0[r] = fmaf(p0[r], C, mnC); for (int r = 0; r < 16; ++r) p1[r] = fmaf(p1[r], C, mnC);
;   for (int r = 0; r < 16; ++r) p0[r] = __builtin_amdgcn_exp2f(p0[r]);
; DI void attn_dense_body(const bf16_t* __restrict__ Qb, const bf16_t* __restrict__ Kh, const bf16_t* __restrict__ Vh, ...
;     ...
;     pv_d0(o, vb0 + (int)SHM_V, pa0, pa1, pa2, pa3); partialSM(pA0, pA1, m_reg, mnA, alA);
;     __syncthreads(); SWAIT(); SWRITE(1, SO);
;     RESC(alA); __syncthreads();
.LBB0_841:
	ds_read_b64_tr_b16 v[232:233], v201 offset:0
	ds_read_b64_tr_b16 v[234:235], v201 offset:0x800
	ds_read_b64_tr_b16 v[236:237], v201 offset:0x1000
	ds_read_b64_tr_b16 v[238:239], v201 offset:0x1800
	ds_read_b64_tr_b16 v[240:241], v201 offset:0x2000
	ds_read_b64_tr_b16 v[242:243], v201 offset:0x2800
	ds_read_b64_tr_b16 v[244:245], v201 offset:0x3000
	ds_read_b64_tr_b16 v[246:247], v201 offset:0x3800
	s_waitcnt lgkmcnt(6)
	s_nop 0
	v_mfma_f32_32x32x16_bf16 v[0:15], v[160:163], v[232:235], v[0:15]
	v_max_f32_e32 v248, v81, v81
	v_max_f32_e32 v249, v80, v80
	v_max_f32_e32 v248, v249, v248
	v_max3_f32 v248, v248, v82, v83
	v_max3_f32 v248, v248, v84, v85
	v_max3_f32 v248, v248, v86, v87
	v_max3_f32 v248, v248, v88, v89
	v_max3_f32 v248, v248, v90, v91
	v_max3_f32 v248, v248, v92, v93
	ds_read_b64_tr_b16 v[232:233], v201 offset:0x200
	ds_read_b64_tr_b16 v[234:235], v201 offset:0xa00
	s_waitcnt lgkmcnt(6)
	v_mfma_f32_32x32x16_bf16 v[0:15], v[164:167], v[236:239], v[0:15]
	v_max3_f32 v248, v248, v94, v95
	v_max3_f32 v248, v248, v64, v65
	v_max3_f32 v248, v248, v66, v67
	v_max3_f32 v248, v248, v68, v69
	v_max3_f32 v248, v248, v70, v71
	v_max3_f32 v248, v248, v72, v73
	v_max3_f32 v248, v248, v74, v75
	v_max3_f32 v248, v248, v76, v77
	ds_read_b64_tr_b16 v[236:237], v201 offset:0x1200
	ds_read_b64_tr_b16 v[238:239], v201 offset:0x1a00
	s_waitcnt lgkmcnt(6)
	v_mfma_f32_32x32x16_bf16 v[0:15], v[168:171], v[240:243], v[0:15]
	v_max3_f32 v248, v248, v78, v79
	v_mov_b32_e32 v249, v248
	s_nop 1
	v_permlane32_swap_b32_e32 v248, v249
	v_max_f32_e32 v249, v249, v249
	v_max_f32_e32 v248, v248, v248
	v_max_f32_e32 v248, v248, v249
	v_sub_f32_e32 v249, v248, v219
	v_cmp_ge_f32_e32 vcc, s95, v249
	v_max_f32_e32 v249, v219, v219
	v_max_f32_e32 v249, v249, v248
	ds_read_b64_tr_b16 v[240:241], v201 offset:0x2200
	ds_read_b64_tr_b16 v[242:243], v201 offset:0x2a00
	s_waitcnt lgkmcnt(6)
	v_mfma_f32_32x32x16_bf16 v[0:15], v[172:175], v[244:247], v[0:15]
	v_sub_f32_e32 v248, v219, v249
	v_mul_f32_e32 v248, 0x3e0293ee, v248
	v_exp_f32_e32 v248, v248
	s_cmp_eq_u64 vcc, exec
	s_cselect_b64 s[0:1], -1, 0
	v_cndmask_b32_e64 v250, v249, v219, s[0:1]
	v_mul_f32_e32 v251, 0xbe0293ee, v250
	ds_read_b64_tr_b16 v[244:245], v201 offset:0x3200
	ds_read_b64_tr_b16 v[246:247], v201 offset:0x3a00
	s_waitcnt lgkmcnt(6)
	v_mfma_f32_32x32x16_bf16 v[48:63], v[160:163], v[232:235], v[48:63]
	v_fmamk_f32 v80, v80, 0x3e0293ee, v251
	v_fmamk_f32 v81, v81, 0x3e0293ee, v251
	v_fmamk_f32 v82, v82, 0x3e0293ee, v251
	v_fmamk_f32 v83, v83, 0x3e0293ee, v251
	ds_read_b64_tr_b16 v[232:233], v201 offset:0x400
	ds_read_b64_tr_b16 v[234:235], v201 offset:0xc00
	s_waitcnt lgkmcnt(6)
	v_mfma_f32_32x32x16_bf16 v[48:63], v[164:167], v[236:239], v[48:63]
	v_fmamk_f32 v84, v84, 0x3e0293ee, v251
	v_fmamk_f32 v85, v85, 0x3e0293ee, v251
	v_fmamk_f32 v86, v86, 0x3e0293ee, v251
	v_fmamk_f32 v87, v87, 0x3e0293ee, v251
	ds_read_b64_tr_b16 v[236:237], v201 offset:0x1400
	ds_read_b64_tr_b16 v[238:239], v201 offset:0x1c00
	s_waitcnt lgkmcnt(6)
	v_mfma_f32_32x32x16_bf16 v[48:63], v[168:171], v[240:243], v[48:63]
	v_fmamk_f32 v88, v88, 0x3e0293ee, v251
	v_fmamk_f32 v89, v89, 0x3e0293ee, v251
	v_fmamk_f32 v90, v90, 0x3e0293ee, v251
	v_fmamk_f32 v91, v91, 0x3e0293ee, v251
	ds_read_b64_tr_b16 v[240:241], v201 offset:0x2400
	ds_read_b64_tr_b16 v[242:243], v201 offset:0x2c00
	s_waitcnt lgkmcnt(6)
	v_mfma_f32_32x32x16_bf16 v[48:63], v[172:175], v[244:247], v[48:63]
	v_fmamk_f32 v92, v92, 0x3e0293ee, v251
	v_fmamk_f32 v93, v93, 0x3e0293ee, v251
	v_fmamk_f32 v94, v94, 0x3e0293ee, v251
	v_fmamk_f32 v95, v95, 0x3e0293ee, v251
	ds_read_b64_tr_b16 v[244:245], v201 offset:0x3400
	ds_read_b64_tr_b16 v[246:247], v201 offset:0x3c00
	s_waitcnt lgkmcnt(6)
	v_mfma_f32_32x32x16_bf16 v[32:47], v[160:163], v[232:235], v[32:47]
	v_exp_f32_e32 v80, v80
	v_exp_f32_e32 v81, v81
	ds_read_b64_tr_b16 v[232:233], v201 offset:0x600
	ds_read_b64_tr_b16 v[234:235], v201 offset:0xe00
	s_waitcnt lgkmcnt(6)
	v_mfma_f32_32x32x16_bf16 v[32:47], v[164:167], v[236:239], v[32:47]
	v_exp_f32_e32 v82, v82
	v_exp_f32_e32 v83, v83
	ds_read_b64_tr_b16 v[236:237], v201 offset:0x1600
	ds_read_b64_tr_b16 v[238:239], v201 offset:0x1e00
	s_waitcnt lgkmcnt(6)
	v_mfma_f32_32x32x16_bf16 v[32:47], v[168:171], v[240:243], v[32:47]
	v_exp_f32_e32 v84, v84
	v_exp_f32_e32 v85, v85
	ds_read_b64_tr_b16 v[240:241], v201 offset:0x2600
	ds_read_b64_tr_b16 v[242:243], v201 offset:0x2e00
	s_waitcnt lgkmcnt(6)
	v_mfma_f32_32x32x16_bf16 v[32:47], v[172:175], v[244:247], v[32:47]
	v_exp_f32_e32 v86, v86
	v_exp_f32_e32 v87, v87
	ds_read_b64_tr_b16 v[244:245], v201 offset:0x3600
	ds_read_b64_tr_b16 v[246:247], v201 offset:0x3e00
	s_waitcnt lgkmcnt(6)
	v_mfma_f32_32x32x16_bf16 v[16:31], v[160:163], v[232:235], v[16:31]
	v_exp_f32_e32 v88, v88
	v_exp_f32_e32 v89, v89
	s_waitcnt lgkmcnt(4)
	v_mfma_f32_32x32x16_bf16 v[16:31], v[164:167], v[236:239], v[16:31]
	v_exp_f32_e32 v90, v90
	v_exp_f32_e32 v91, v91
	s_waitcnt lgkmcnt(2)
	v_mfma_f32_32x32x16_bf16 v[16:31], v[168:171], v[240:243], v[16:31]
	v_exp_f32_e32 v92, v92
	v_exp_f32_e32 v93, v93
	s_waitcnt lgkmcnt(0)
	v_mfma_f32_32x32x16_bf16 v[16:31], v[172:175], v[244:247], v[16:31]
	v_exp_f32_e32 v94, v94
	v_exp_f32_e32 v95, v95
	s_barrier
; #define SWRITE(b, i) do { *(bf16x8*)((char*)V_lds + (b) * SHM_V + vst0) = sr_[i].vs0;          \
;     *(bf16x8*)((char*)V_lds + (b) * SHM_V + vst1) = sr_[i].vs1; int kc = sc * 2;               \
;     *(bf16x8*)((char*)K_lds + (b) * SHM_K + KSWZ(sr, kc)) = sr_[i].ks0;                       \
;     *(bf16x8*)((char*)K_lds + (b) * SHM_K + KSWZ(32 + sr, kc)) = sr_[i].ks1; } while (0)
; #define SWAIT() asm volatile("s_waitcnt vmcnt(4)" ::: "memory")
; #define RESC(a) do { if (__any((a) < 1.f)) { if (hi == 0) al_l[r32] = (a); asm volatile("s_waitcnt lgkmcnt(0)" ::: "memory"); \
;     for (int d = 0; d < 4; ++d) for (int r = 0; r < 16; ++r) o[d][r] *= al_l[crow(r, hi)]; } } while (0)
; DI void partialSM(f32x16& p0, f32x16& p1, float& m_reg, float& mn, float& alpha) {
;     ...
;   for (int r = 0; r < 16; ++r) p0[r] = fmaf(p0[r], C, mnC); for (int r = 0; r < 16; ++r) p1[r] = fmaf(p1[r], C, mnC);
;   for (int r = 0; r < 16; ++r) p0[r] = __builtin_amdgcn_exp2f(p0[r]);
; }
; DI void finishSM(f32x16& p0, f32x16& p1, float alpha, float& l_reg, bf16x8& pa0, bf16x8& pa1, bf16x8& pa2, bf16x8& pa3) {
;   for (int r = 0; r < 16; ++r) p1[r] = __builtin_amdgcn_exp2f(p1[r]);
;   float ps = 0; for (int r = 0; r < 16; ++r) ps += p0[r]; for (int r = 0; r < 16; ++r) ps += p1[r];
;   { auto rr = __builtin_amdgcn_permlane32_swap(__float_as_uint(ps), __float_as_uint(ps), false, false);
;     ps = __uint_as_float(rr[0]) + __uint_as_float(rr[1]); }
;   l_reg = l_reg * alpha + ps;
; DI void attn_dense_body(const bf16_t* __restrict__ Qb, const bf16_t* __restrict__ Kh, const bf16_t* __restrict__ Vh, ...
;     ...
;     __syncthreads(); SWAIT(); SWRITE(1, SO);
;     RESC(alA); __syncthreads();
	s_waitcnt vmcnt(4)
	v_cndmask_b32_e64 v160, v248, 1.0, s[0:1]
	v_cmp_gt_f32_e32 vcc, 1.0, v160
	ds_write_b128 v204, v[144:147] offset:16384
	ds_write_b128 v205, v[148:151] offset:16384
	s_cbranch_vccz .LBB0_845
	s_and_saveexec_b64 s[12:13], s[4:5]
	ds_write_b32 v199, v160 offset:128
	s_or_b64 exec, exec, s[12:13]
	s_waitcnt lgkmcnt(0)
	v_add_u32_e32 v156, v198, v180
	ds_read_b128 v[144:147], v156 offset:224
	ds_read_b128 v[148:151], v156 offset:192
	ds_read_b128 v[152:155], v156 offset:160
	ds_read_b128 v[156:159], v156 offset:128
	s_waitcnt lgkmcnt(3)
	v_pk_mul_f32 v[12:13], v[12:13], v[144:145]
	s_waitcnt lgkmcnt(2)
	v_pk_mul_f32 v[8:9], v[8:9], v[148:149]
	s_waitcnt lgkmcnt(1)
	v_pk_mul_f32 v[4:5], v[4:5], v[152:153]
	v_pk_mul_f32 v[14:15], v[14:15], v[146:147]
	v_pk_mul_f32 v[10:11], v[10:11], v[150:151]
	v_pk_mul_f32 v[6:7], v[6:7], v[154:155]
	s_waitcnt lgkmcnt(0)
	v_pk_mul_f32 v[2:3], v[2:3], v[158:159]
	v_pk_mul_f32 v[0:1], v[0:1], v[156:157]
	v_pk_mul_f32 v[60:61], v[60:61], v[144:145]
	v_pk_mul_f32 v[56:57], v[56:57], v[148:149]
	v_pk_mul_f32 v[52:53], v[52:53], v[152:153]
	v_pk_mul_f32 v[62:63], v[62:63], v[146:147]
	v_pk_mul_f32 v[58:59], v[58:59], v[150:151]
	v_pk_mul_f32 v[54:55], v[54:55], v[154:155]
	v_pk_mul_f32 v[50:51], v[50:51], v[158:159]
	v_pk_mul_f32 v[48:49], v[48:49], v[156:157]
	v_pk_mul_f32 v[44:45], v[44:45], v[144:145]
	v_pk_mul_f32 v[40:41], v[40:41], v[148:149]
	v_pk_mul_f32 v[36:37], v[36:37], v[152:153]
	v_pk_mul_f32 v[46:47], v[46:47], v[146:147]
	v_pk_mul_f32 v[42:43], v[42:43], v[150:151]
	v_pk_mul_f32 v[38:39], v[38:39], v[154:155]
	v_pk_mul_f32 v[34:35], v[34:35], v[158:159]
	v_pk_mul_f32 v[32:33], v[32:33], v[156:157]
	v_pk_mul_f32 v[28:29], v[28:29], v[144:145]
	v_pk_mul_f32 v[24:25], v[24:25], v[148:149]
	v_pk_mul_f32 v[20:21], v[20:21], v[152:153]
	v_pk_mul_f32 v[30:31], v[30:31], v[146:147]
	v_pk_mul_f32 v[26:27], v[26:27], v[150:151]
	v_pk_mul_f32 v[22:23], v[22:23], v[154:155]
	v_pk_mul_f32 v[18:19], v[18:19], v[158:159]
	v_pk_mul_f32 v[16:17], v[16:17], v[156:157]
.LBB0_845:
	v_mov_b32_e32 v168, v250
	v_mov_b32_e32 v144, v251
	v_mov_b32_e32 v145, v144
	v_mov_b32_e32 v161, v80
	v_mov_b32_e32 v175, v81
	v_mov_b32_e32 v162, v82
	v_mov_b32_e32 v219, v83
	v_mov_b32_e32 v174, v84
	v_mov_b32_e32 v222, v85
	v_mov_b32_e32 v163, v86
	v_mov_b32_e32 v173, v87
	v_mov_b32_e32 v164, v88
	v_mov_b32_e32 v171, v89
	v_mov_b32_e32 v165, v90
	v_mov_b32_e32 v172, v91
	v_mov_b32_e32 v166, v92
	v_mov_b32_e32 v169, v93
	v_mov_b32_e32 v167, v94
	v_mov_b32_e32 v170, v95
	v_pk_fma_f32 v[158:159], v[64:65], s[42:43], v[144:145] op_sel_hi:[1,0,0]
	v_add_f32_e32 v64, v216, v217
	v_fmac_f32_e32 v64, v215, v200
	v_add_f32_e32 v200, v220, v221
	s_mov_b64 s[0:1], 0x10000
	v_pk_fma_f32 v[156:157], v[66:67], s[42:43], v[144:145] op_sel_hi:[1,0,0]
	v_pk_fma_f32 v[152:153], v[68:69], s[42:43], v[144:145] op_sel_hi:[1,0,0]
	v_pk_fma_f32 v[148:149], v[70:71], s[42:43], v[144:145] op_sel_hi:[1,0,0]
	v_pk_fma_f32 v[146:147], v[72:73], s[42:43], v[144:145] op_sel_hi:[1,0,0]
	v_pk_fma_f32 v[154:155], v[74:75], s[42:43], v[144:145] op_sel_hi:[1,0,0]
	v_pk_fma_f32 v[150:151], v[76:77], s[42:43], v[144:145] op_sel_hi:[1,0,0]
	v_pk_fma_f32 v[144:145], v[78:79], s[42:43], v[144:145] op_sel_hi:[1,0,0]
	v_fmac_f32_e32 v200, v64, v218
	v_lshl_add_u64 v[194:195], v[194:195], 0, s[0:1]
	s_add_i32 s16, s16, 2
	s_and_b64 vcc, exec, s[10:11]
	s_waitcnt lgkmcnt(0)
	s_cbranch_vccnz .LBB0_847
	v_mov_b32_e32 v215, v160
	s_branch .LBB0_835
